# P6 out-proj GEMM k-loop also converted to 3-stage LDS-DMA pipeline
# speedup vs baseline: 1.0427x; 1.0059x over previous
; DEVI int TID() { int t = threadIdx.x; asm volatile("" : "+v"(t)); return t; }
;   const int tid = TID(), lane = tid & 63, wave = tid >> 6;
;   const int l15 = lane & 15, quad = lane >> 4;
;   const int wm = wave >> 1, wn = wave & 1;
;   const int TM = KS > 0 ? 128 : NTOK / 256;
;   const int total = TM * TN + (KS > 0 ? TN * KS : 0);
;   const int nkfull = K / 32;
;   const int ldrow = tid >> 2, ldp = tid & 3;
;   const int lsw = ((ldp ^ ((ldrow >> 2) & 3)) * 16);
;   const int rsw = ((quad ^ ((l15 >> 2) & 3)) * 16);
;   const int nfullp = TN >> 3;
;     ...
;     const u16* Ag = A + (size_t)(m0 + ldrow) * K + ldp * 8 + kt0 * 32;
;     const u16* Bg = Bt + (size_t)(n0 + ldrow) * K + ldp * 8 + kt0 * 32;
.LBB0_1295:
	s_or_b64 exec, exec, s[2:3]
	v_mov_b32_e32 v6, v1
	s_barrier
	v_readlane_b32 s2, v251, 56
	v_lshrrev_b32_e32 v4, 4, v6
	v_lshrrev_b32_e32 v9, 2, v6
	v_xor_b32_e32 v4, v4, v9
	v_lshlrev_b32_e32 v5, 4, v6
	v_lshlrev_b32_e32 v4, 4, v4
	v_bitop3_b32 v8, v5, 48, v6 bitop3:0x48
	v_and_b32_e32 v10, 48, v4
	v_and_b32_e32 v4, 48, v5
	v_mov_b32_e32 v5, v2
	v_readlane_b32 s3, v251, 57
	v_ashrrev_i32_e32 v3, 2, v6
	v_bfe_u32 v7, v6, 6, 1
	v_lshl_add_u64 v[132:133], s[2:3], 0, v[4:5]
	v_readlane_b32 s2, v251, 54
	v_readlane_b32 s3, v251, 55
	v_add_u32_e32 v8, 0, v8
	v_and_b32_e32 v146, 0xffffff8f, v6
	v_lshl_add_u64 v[134:135], s[2:3], 0, v[4:5]
	v_lshlrev_b32_e32 v4, 6, v3
	v_and_b32_e32 v5, 12, v9
	v_lshl_or_b32 v147, v7, 6, v5
	v_lshlrev_b32_e32 v5, 6, v6
	v_add_u32_e32 v152, v8, v4
	v_and_b32_e32 v4, 3, v6
	v_readlane_b32 s2, v251, 1
	v_and_b32_e32 v149, 0x3c0, v5
	v_and_b32_e32 v150, 0xffffe3c0, v5
	v_lshlrev_b32_e32 v4, 4, v4
	v_mov_b32_e32 v5, v2
	v_readlane_b32 s3, v251, 2
	v_lshlrev_b32_e32 v148, 12, v7
	v_add_u32_e32 v151, 0, v10
	v_lshl_add_u64 v[136:137], s[2:3], 0, v[4:5]
	s_mov_b32 s2, 0
	s_mov_b32 s8, 0
	v_writelane_b32 v255, s28, 45
	v_writelane_b32 v255, s29, 46
	v_writelane_b32 v255, s30, 47
	v_writelane_b32 v255, s31, 48
	v_lshrrev_b32_e32 v4, 6, v1
	v_lshrrev_b32_e32 v5, 4, v1
	v_xor_b32_e32 v5, v5, v1
	v_readfirstlane_b32 s28, v4
	v_and_b32_e32 v5, 3, v5
	v_and_b32_e32 v4, 3, v1
	v_sub_u32_e32 v4, v5, v4
	v_lshlrev_b32_e32 v4, 4, v4
	v_ashrrev_i32_e32 v5, 31, v4
	s_lshl_b32 s28, s28, 10
	v_lshl_add_u64 v[132:133], v[132:133], 0, v[4:5]
	v_lshl_add_u64 v[134:135], v[134:135], 0, v[4:5]
	v_lshl_add_u64 v[136:137], v[136:137], 0, v[4:5]
	s_branch .LBB0_1297

;     ...
;   for (int rnd = 0; rnd * nb < total; ++rnd) {
;     const int id = rnd * nb + (bid & 7) * (nb >> 3) + (bid >> 3);
;     if (id >= total) continue;
;     int tm, tn;
;     int kt0 = 0, nk = nkfull;
;     bool split = false;
;     if (id >= TM * TN) {
;       const int piece = id - TM * TN;
;       tn = piece / KS;
;       const int ks = piece - tn * KS;
;       tm = 128;
;       nk = nkfull / KS;
;       kt0 = ks * nk;
;       split = true;
;     } else {
;       const int pan = id / (TM * 8);
;       if (pan < nfullp) {
;         const int r = id - pan * (TM * 8);
;         tm = r >> 3; tn = pan * 8 + (r & 7);
;       } else {
;         const int pw = TN - nfullp * 8;
;         const int r = id - nfullp * (TM * 8);
;         tm = r / pw; tn = nfullp * 8 + r % pw;
;       }
;     }
;     const int m0 = tm * 256, n0 = tn * 128;
;     f32x4 acc[8][4];
; #pragma unroll
;     for (int i = 0; i < 8; ++i)
; #pragma unroll
;       for (int j = 0; j < 4; ++j) acc[i][j] = f32x4{0.f, 0.f, 0.f, 0.f};
;     u32x4 ra[4], rb[2];
;     const u16* Ag = A + (size_t)(m0 + ldrow) * K + ldp * 8 + kt0 * 32;
;     const u16* Bg = Bt + (size_t)(n0 + ldrow) * K + ldp * 8 + kt0 * 32;
; #pragma unroll
;     for (int i = 0; i < 4; ++i) ra[i] = *(const u32x4*)(Ag + (size_t)(i * 64) * K);
; #pragma unroll
;     for (int i = 0; i < 2; ++i) rb[i] = *(const u32x4*)(Bg + (size_t)(i * 64) * K);
;     __syncthreads();
; #pragma unroll
;     for (int i = 0; i < 4; ++i) *(u32x4*)(smem + (ldrow + i * 64) * 64 + lsw) = ra[i];
; #pragma unroll
;     for (int i = 0; i < 2; ++i) *(u32x4*)(smem + 16384 + (ldrow + i * 64) * 64 + lsw) = rb[i];
;     __syncthreads();
.LBB0_1302:
	v_add_u32_e32 v4, s9, v3
	v_ashrrev_i32_e32 v5, 31, v4
	s_waitcnt vmcnt(3)
	v_lshlrev_b64 v[64:65], 12, v[4:5]
	v_lshl_add_u64 v[4:5], v[132:133], 0, v[64:65]
	s_lshl_b64 s[4:5], s[4:5], 1
	v_lshl_add_u64 v[4:5], v[4:5], 0, s[4:5]
	s_mov_b32 s13, 0x40000
	v_add_co_u32_e32 v8, vcc, s13, v4
	s_lshl_b32 s10, s11, 7
	s_nop 0
	v_addc_co_u32_e32 v9, vcc, 0, v5, vcc
	s_mov_b32 s11, 0x80000
	v_add_u32_e32 v6, s10, v3
	s_barrier
	s_mov_b32 m0, s28
	s_nop 0
	global_load_lds_dwordx4 v[4:5], off
	s_add_u32 m0, s28, 0x5fc0
	s_nop 0
	global_load_lds_dwordx4 v[4:5], off offset:64
	s_add_u32 m0, s28, 0x1000
	s_nop 0
	global_load_lds_dwordx4 v[8:9], off
	s_add_u32 m0, s28, 0x6fc0
	s_nop 0
	global_load_lds_dwordx4 v[8:9], off offset:64
	v_add_co_u32_e32 v8, vcc, s11, v4
	v_ashrrev_i32_e32 v7, 31, v6
	s_nop 0
	v_addc_co_u32_e32 v9, vcc, 0, v5, vcc
	s_mov_b32 s11, 0xc0000
	v_lshlrev_b64 v[66:67], 12, v[6:7]
	v_add_co_u32_e32 v4, vcc, s11, v4
	v_lshl_add_u64 v[6:7], v[134:135], 0, v[66:67]
	s_nop 0
	v_addc_co_u32_e32 v5, vcc, 0, v5, vcc
	s_add_u32 m0, s28, 0x2000
	s_nop 0
	global_load_lds_dwordx4 v[8:9], off
	s_add_u32 m0, s28, 0x7fc0
	s_nop 0
	global_load_lds_dwordx4 v[8:9], off offset:64
	s_add_u32 m0, s28, 0x3000
	s_nop 0
	global_load_lds_dwordx4 v[4:5], off
	s_add_u32 m0, s28, 0x8fc0
	s_nop 0
	global_load_lds_dwordx4 v[4:5], off offset:64
	v_lshl_add_u64 v[4:5], v[6:7], 0, s[4:5]
	v_add_co_u32_e32 v6, vcc, s13, v4
	v_lshl_add_u64 v[64:65], v[64:65], 0, s[4:5]
	s_nop 0
	v_addc_co_u32_e32 v7, vcc, 0, v5, vcc
	s_add_u32 m0, s28, 0x4000
	s_nop 0
	global_load_lds_dwordx4 v[4:5], off
	s_add_u32 m0, s28, 0x9fc0
	s_nop 0
	global_load_lds_dwordx4 v[4:5], off offset:64
	s_add_u32 m0, s28, 0x5000
	s_nop 0
	global_load_lds_dwordx4 v[6:7], off
	s_add_u32 m0, s28, 0xafc0
	s_nop 0
	global_load_lds_dwordx4 v[6:7], off offset:64
	s_lshl_b32 s12, s12, 6
	v_mov_b32_e32 v4, 0
	v_lshl_add_u64 v[138:139], v[136:137], 0, v[64:65]
	v_lshl_add_u64 v[64:65], v[66:67], 0, s[4:5]
	s_mov_b32 s11, 0
	s_add_u32 s12, s12, 0xc0
	v_mov_b32_e32 v5, v4
	v_mov_b32_e32 v6, v4
	v_mov_b32_e32 v7, v4
	v_mov_b32_e32 v8, v4
	v_mov_b32_e32 v9, v4
	v_mov_b32_e32 v10, v4
	v_mov_b32_e32 v11, v4
	v_mov_b32_e32 v12, v4
	v_mov_b32_e32 v13, v4
	v_mov_b32_e32 v14, v4
	v_mov_b32_e32 v15, v4
	v_mov_b32_e32 v16, v4
	v_mov_b32_e32 v17, v4
	v_mov_b32_e32 v18, v4
	v_mov_b32_e32 v19, v4
	v_mov_b32_e32 v20, v4
	v_mov_b32_e32 v21, v4
	v_mov_b32_e32 v22, v4
	v_mov_b32_e32 v23, v4
	v_mov_b32_e32 v24, v4
	v_mov_b32_e32 v25, v4
	v_mov_b32_e32 v26, v4
	v_mov_b32_e32 v27, v4
	v_mov_b32_e32 v28, v4
	v_mov_b32_e32 v29, v4
	v_mov_b32_e32 v30, v4
	v_mov_b32_e32 v31, v4
	v_mov_b32_e32 v32, v4
	v_mov_b32_e32 v33, v4
	v_mov_b32_e32 v34, v4
	v_mov_b32_e32 v35, v4
	v_mov_b32_e32 v36, v4
	v_mov_b32_e32 v37, v4
	v_mov_b32_e32 v38, v4
	v_lshl_add_u64 v[140:141], v[136:137], 0, v[64:65]
	v_mov_b32_e32 v39, v4
	v_mov_b32_e32 v64, v4
	v_mov_b32_e32 v65, v4
	v_mov_b32_e32 v66, v4
	v_mov_b32_e32 v67, v4
	v_mov_b32_e32 v68, v4
	v_mov_b32_e32 v69, v4
	v_mov_b32_e32 v70, v4
	v_mov_b32_e32 v71, v4
	v_mov_b32_e32 v72, v4
	v_mov_b32_e32 v73, v4
	v_mov_b32_e32 v74, v4
	v_mov_b32_e32 v75, v4
	v_mov_b32_e32 v76, v4
	v_mov_b32_e32 v40, v4
	v_mov_b32_e32 v41, v4
	v_mov_b32_e32 v42, v4
	v_mov_b32_e32 v43, v4
	v_mov_b32_e32 v44, v4
	v_mov_b32_e32 v45, v4
	v_mov_b32_e32 v46, v4
	v_mov_b32_e32 v47, v4
	v_mov_b32_e32 v48, v4
	v_mov_b32_e32 v49, v4
	v_mov_b32_e32 v50, v4
	v_mov_b32_e32 v51, v4
	v_mov_b32_e32 v52, v4
	v_mov_b32_e32 v53, v4
	v_mov_b32_e32 v54, v4
	v_mov_b32_e32 v55, v4
	v_mov_b32_e32 v56, v4
	v_mov_b32_e32 v57, v4
	v_mov_b32_e32 v58, v4
	v_mov_b32_e32 v59, v4
	v_mov_b32_e32 v60, v4
	v_mov_b32_e32 v61, v4
	v_mov_b32_e32 v62, v4
	v_mov_b32_e32 v63, v4
	v_mov_b32_e32 v77, v4
	v_mov_b32_e32 v78, v4
	v_mov_b32_e32 v79, v4
	v_mov_b32_e32 v80, v4
	v_mov_b32_e32 v81, v4
	v_mov_b32_e32 v82, v4
	v_mov_b32_e32 v83, v4
	v_mov_b32_e32 v84, v4
	v_mov_b32_e32 v85, v4
	v_mov_b32_e32 v86, v4
	v_mov_b32_e32 v87, v4
	v_mov_b32_e32 v88, v4
	v_mov_b32_e32 v89, v4
	v_mov_b32_e32 v90, v4
	v_mov_b32_e32 v91, v4
	v_mov_b32_e32 v92, v4
	v_mov_b32_e32 v93, v4
	v_mov_b32_e32 v94, v4
	v_mov_b32_e32 v95, v4
	v_mov_b32_e32 v96, v4
	v_mov_b32_e32 v97, v4
	v_mov_b32_e32 v98, v4
	v_mov_b32_e32 v99, v4
	v_mov_b32_e32 v100, v4
	v_mov_b32_e32 v101, v4
	v_mov_b32_e32 v102, v4
	v_mov_b32_e32 v103, v4
	v_mov_b32_e32 v104, v4
	v_mov_b32_e32 v105, v4
	v_mov_b32_e32 v106, v4
	v_mov_b32_e32 v107, v4
	v_mov_b32_e32 v108, v4
	v_mov_b32_e32 v109, v4
	v_mov_b32_e32 v110, v4
	v_mov_b32_e32 v111, v4
	v_mov_b32_e32 v112, v4
	v_mov_b32_e32 v113, v4
	v_mov_b32_e32 v114, v4
	v_mov_b32_e32 v115, v4
	v_mov_b32_e32 v116, v4
	v_mov_b32_e32 v117, v4
	v_mov_b32_e32 v118, v4
	v_mov_b32_e32 v119, v4
	v_mov_b32_e32 v120, v4
	v_mov_b32_e32 v121, v4
	v_mov_b32_e32 v122, v4
	v_mov_b32_e32 v123, v4
	v_mov_b32_e32 v124, v4
	v_mov_b32_e32 v125, v4
	v_mov_b32_e32 v126, v4
	v_mov_b32_e32 v127, v4
	v_mov_b32_e32 v128, v4
	v_mov_b32_e32 v129, v4
	v_mov_b32_e32 v130, v4
	v_mov_b32_e32 v131, v4
	s_mov_b32 s13, 0x2480000
	s_mov_b32 s14, 0x24c0000
	s_mov_b32 s15, 0x2500000
	s_mov_b32 s16, 0x2540000
	s_mov_b64 s[2:3], 0x80
	s_mov_b32 s29, 0
	s_mov_b32 s30, 0xc000
	s_waitcnt vmcnt(0) lgkmcnt(0)
	s_barrier
;     ...
;     for (int kt = 0; kt < nk; ++kt) {
;       const int buf = kt & 1;
;       if (kt + 1 < nk) {
; #pragma unroll
;         for (int i = 0; i < 4; ++i) ra[i] = *(const u32x4*)(Ag + (size_t)(i * 64) * K + (kt + 1) * 32);
; #pragma unroll
;         for (int i = 0; i < 2; ++i) rb[i] = *(const u32x4*)(Bg + (size_t)(i * 64) * K + (kt + 1) * 32);
;       }
;       const char* As = smem + buf * 24576;
;       const char* Bs = As + 16384;
;       bf16x8 bfr[4];
; #pragma unroll
;       for (int j = 0; j < 4; ++j) bfr[j] = *(const bf16x8*)(Bs + (wn * 64 + j * 16 + l15) * 64 + rsw);
;       bf16x8 afr[8];
; #pragma unroll
;       for (int i = 0; i < 8; ++i) afr[i] = *(const bf16x8*)(As + (wm * 128 + i * 16 + l15) * 64 + rsw);
;       __builtin_amdgcn_s_setprio(1);
; #pragma unroll
;       for (int i = 0; i < 8; ++i) {
; #pragma unroll
;         for (int j = 0; j < 4; ++j) acc[i][j] = __builtin_amdgcn_mfma_f32_16x16x32_bf16(bfr[j], afr[i], acc[i][j], 0, 0, 0);
;       }
;       __builtin_amdgcn_s_setprio(0);
;       if (kt + 1 < nk) {
;         char* Aw = smem + (buf ^ 1) * 24576;
;         char* Bw = Aw + 16384;
; #pragma unroll
;         for (int i = 0; i < 4; ++i) *(u32x4*)(Aw + (ldrow + i * 64) * 64 + lsw) = ra[i];
; #pragma unroll
;         for (int i = 0; i < 2; ++i) *(u32x4*)(Bw + (ldrow + i * 64) * 64 + lsw) = rb[i];
;       }
;       __syncthreads();
;     }
.LBB0_1303:
	s_add_u32 s31, s30, s28
	v_lshl_add_u64 v[142:143], v[138:139], 0, s[2:3]
	v_add_co_u32_e32 v154, vcc, s13, v142
	v_lshl_add_u64 v[144:145], v[140:141], 0, s[2:3]
	s_nop 0
	v_addc_co_u32_e32 v155, vcc, 0, v143, vcc
	v_add_co_u32_e32 v156, vcc, s14, v142
	s_mov_b32 s4, 0x1c80000
	s_nop 0
	v_addc_co_u32_e32 v157, vcc, 0, v143, vcc
	v_add_co_u32_e32 v158, vcc, s15, v142
	s_nop 1
	v_addc_co_u32_e32 v159, vcc, 0, v143, vcc
	v_add_co_u32_e32 v162, vcc, s16, v142
	s_nop 1
	v_addc_co_u32_e32 v163, vcc, 0, v143, vcc
	v_add_co_u32_e32 v166, vcc, s4, v144
	s_mov_b32 s4, 0x1cc0000
	s_nop 0
	v_addc_co_u32_e32 v167, vcc, 0, v145, vcc
	v_add_co_u32_e32 v170, vcc, s4, v144
	s_and_b32 s4, s11, 1
	s_nop 0
	v_addc_co_u32_e32 v171, vcc, 0, v145, vcc
	s_mov_b32 m0, s31
	s_nop 0
	global_load_lds_dwordx4 v[154:155], off
	s_nop 0
	s_add_u32 m0, s31, 0x1000
	s_nop 0
	global_load_lds_dwordx4 v[156:157], off
	s_nop 0
	s_add_u32 m0, s31, 0x2000
	s_nop 0
	global_load_lds_dwordx4 v[158:159], off
	s_nop 0
	s_add_u32 m0, s31, 0x3000
	s_nop 0
	global_load_lds_dwordx4 v[162:163], off
	s_nop 0
	s_add_u32 m0, s31, 0x4000
	s_nop 0
	global_load_lds_dwordx4 v[166:167], off
	s_nop 0
	s_add_u32 m0, s31, 0x5000
	s_nop 0
	global_load_lds_dwordx4 v[170:171], off
	v_add_u32_e32 v153, s29, v151
	v_add3_u32 v186, v153, v148, v149
	v_add_u32_e32 v153, v153, v150
	ds_read_b128 v[174:177], v186 offset:16384
	ds_read_b128 v[178:181], v186 offset:17408
	ds_read_b128 v[182:185], v186 offset:18432
	ds_read_b128 v[186:189], v186 offset:19456
	ds_read_b128 v[190:193], v153
	ds_read_b128 v[194:197], v153 offset:1024
	ds_read_b128 v[198:201], v153 offset:2048
	ds_read_b128 v[210:213], v153 offset:3072
	ds_read_b128 v[220:223], v153 offset:4096
	ds_read_b128 v[224:227], v153 offset:5120
	ds_read_b128 v[230:233], v153 offset:6144
	ds_read_b128 v[234:237], v153 offset:7168
	s_add_i32 s11, s11, 1
	s_setprio 1
	s_waitcnt lgkmcnt(7)
	v_mfma_f32_16x16x32_bf16 v[128:131], v[174:177], v[190:193], v[128:131]
	v_mfma_f32_16x16x32_bf16 v[124:127], v[178:181], v[190:193], v[124:127]
	v_mfma_f32_16x16x32_bf16 v[120:123], v[182:185], v[190:193], v[120:123]
	v_mfma_f32_16x16x32_bf16 v[116:119], v[186:189], v[190:193], v[116:119]
	s_waitcnt lgkmcnt(6)
	v_mfma_f32_16x16x32_bf16 v[112:115], v[174:177], v[194:197], v[112:115]
	v_mfma_f32_16x16x32_bf16 v[108:111], v[178:181], v[194:197], v[108:111]
	v_mfma_f32_16x16x32_bf16 v[104:107], v[182:185], v[194:197], v[104:107]
	v_mfma_f32_16x16x32_bf16 v[100:103], v[186:189], v[194:197], v[100:103]
	s_waitcnt lgkmcnt(5)
	v_mfma_f32_16x16x32_bf16 v[96:99], v[174:177], v[198:201], v[96:99]
	v_mfma_f32_16x16x32_bf16 v[92:95], v[178:181], v[198:201], v[92:95]
	v_mfma_f32_16x16x32_bf16 v[88:91], v[182:185], v[198:201], v[88:91]
	v_mfma_f32_16x16x32_bf16 v[84:87], v[186:189], v[198:201], v[84:87]
	s_waitcnt lgkmcnt(4)
	v_mfma_f32_16x16x32_bf16 v[80:83], v[174:177], v[210:213], v[80:83]
	v_mfma_f32_16x16x32_bf16 v[76:79], v[178:181], v[210:213], v[76:79]
	v_mfma_f32_16x16x32_bf16 v[72:75], v[182:185], v[210:213], v[72:75]
	v_mfma_f32_16x16x32_bf16 v[68:71], v[186:189], v[210:213], v[68:71]
	s_waitcnt lgkmcnt(3)
	v_mfma_f32_16x16x32_bf16 v[64:67], v[174:177], v[220:223], v[64:67]
	v_mfma_f32_16x16x32_bf16 v[60:63], v[178:181], v[220:223], v[60:63]
	v_mfma_f32_16x16x32_bf16 v[56:59], v[182:185], v[220:223], v[56:59]
	v_mfma_f32_16x16x32_bf16 v[52:55], v[186:189], v[220:223], v[52:55]
	s_waitcnt lgkmcnt(2)
	v_mfma_f32_16x16x32_bf16 v[48:51], v[174:177], v[224:227], v[48:51]
	v_mfma_f32_16x16x32_bf16 v[44:47], v[178:181], v[224:227], v[44:47]
	v_mfma_f32_16x16x32_bf16 v[40:43], v[182:185], v[224:227], v[40:43]
	v_mfma_f32_16x16x32_bf16 v[36:39], v[186:189], v[224:227], v[36:39]
	s_waitcnt lgkmcnt(1)
	v_mfma_f32_16x16x32_bf16 v[32:35], v[174:177], v[230:233], v[32:35]
	v_mfma_f32_16x16x32_bf16 v[28:31], v[178:181], v[230:233], v[28:31]
	v_mfma_f32_16x16x32_bf16 v[24:27], v[182:185], v[230:233], v[24:27]
	v_mfma_f32_16x16x32_bf16 v[20:23], v[186:189], v[230:233], v[20:23]
	s_waitcnt lgkmcnt(0)
	v_mfma_f32_16x16x32_bf16 v[16:19], v[174:177], v[234:237], v[16:19]
	v_mfma_f32_16x16x32_bf16 v[12:15], v[178:181], v[234:237], v[12:15]
	v_mfma_f32_16x16x32_bf16 v[8:11], v[182:185], v[234:237], v[8:11]
	v_mfma_f32_16x16x32_bf16 v[4:7], v[186:189], v[234:237], v[4:7]
	s_setprio 0
	s_add_u32 s2, s2, 64
	s_addc_u32 s3, s3, 0
	s_add_u32 s29, s29, 0x6000
	s_cmp_eq_u32 s29, 0x12000
	s_cselect_b32 s29, 0, s29
	s_add_u32 s30, s30, 0x6000
	s_cmp_eq_u32 s30, 0x12000
	s_cselect_b32 s30, 0, s30
	s_cmp_eq_u32 s12, s2
	s_waitcnt vmcnt(6)
	s_barrier
	s_cbranch_scc0 .LBB0_1303
; DEVI u32 pack2(float a, float b) { return f2bf(a) | (f2bf(b) << 16); }
;     ...
;       const char* As = smem + buf * 24576;
;       const char* Bs = As + 16384;
;       bf16x8 bfr[4];
; #pragma unroll
;       for (int j = 0; j < 4; ++j) bfr[j] = *(const bf16x8*)(Bs + (wn * 64 + j * 16 + l15) * 64 + rsw);
;       bf16x8 afr[8];
; #pragma unroll
;       for (int i = 0; i < 8; ++i) afr[i] = *(const bf16x8*)(As + (wm * 128 + i * 16 + l15) * 64 + rsw);
;       __builtin_amdgcn_s_setprio(1);
; #pragma unroll
;       for (int i = 0; i < 8; ++i) {
; #pragma unroll
;         for (int j = 0; j < 4; ++j) acc[i][j] = __builtin_amdgcn_mfma_f32_16x16x32_bf16(bfr[j], afr[i], acc[i][j], 0, 0, 0);
;       }
;       __builtin_amdgcn_s_setprio(0);
;       if (kt + 1 < nk) {
;         char* Aw = smem + (buf ^ 1) * 24576;
;         char* Bw = Aw + 16384;
; #pragma unroll
;         for (int i = 0; i < 4; ++i) *(u32x4*)(Aw + (ldrow + i * 64) * 64 + lsw) = ra[i];
; #pragma unroll
;         for (int i = 0; i < 2; ++i) *(u32x4*)(Bw + (ldrow + i * 64) * 64 + lsw) = rb[i];
;       }
;       __syncthreads();
;     }
; #pragma unroll
;     for (int i = 0; i < 8; ++i) {
;       const int row = m0 + wm * 128 + i * 16 + l15;
; #pragma unroll
;       for (int j = 0; j < 4; ++j) {
;         const int n = n0 + wn * 64 + j * 16 + quad * 4;
;         f32x4 a = acc[i][j];
;         if (EPI == EPI_Z) {
;           u16* dst;
;           if (n0 < 1536) dst = (u16*)(p.ws + W_ZA) + (size_t)row * LZA + n;
;           else if (n0 < 4736) dst = (u16*)(p.ws + W_ZB) + (size_t)row * LZB + (n - 1536);
;           else dst = (u16*)(p.ws + W_ZC) + (size_t)row * LZC + (n - 4736);
;           *(uint2*)dst = make_uint2(pack2(a[0], a[1]), pack2(a[2], a[3]));
;         } else if (EPI == EPI_RES) {
;           if (split) {
;             float* op = p.out + (size_t)row * D + n;
;             unsafeAtomicAdd(op, a[0]); unsafeAtomicAdd(op + 1, a[1]); unsafeAtomicAdd(op + 2, a[2]); unsafeAtomicAdd(op + 3, a[3]);
;           } else {
;             const float* xin = res_from_input ? xrow_in(p, 0, row) : p.out + (size_t)row * D;
;             float4 xv = *(const float4*)(xin + n);
;             float4 o = make_float4(xv.x + a[0], xv.y + a[1], xv.z + a[2], xv.w + a[3]);
;             *(float4*)(p.out + (size_t)row * D + n) = o;
	v_add_u32_e32 v153, s29, v151
	v_add3_u32 v158, v153, v148, v149
	v_add_u32_e32 v153, v153, v150
	ds_read_b128 v[138:141], v158 offset:16384
	ds_read_b128 v[142:145], v158 offset:17408
	ds_read_b128 v[154:157], v158 offset:18432
	ds_read_b128 v[158:161], v158 offset:19456
	ds_read_b128 v[162:165], v153
	ds_read_b128 v[166:169], v153 offset:1024
	ds_read_b128 v[170:173], v153 offset:2048
	ds_read_b128 v[174:177], v153 offset:3072
	ds_read_b128 v[178:181], v153 offset:4096
	ds_read_b128 v[182:185], v153 offset:5120
	ds_read_b128 v[186:189], v153 offset:6144
	ds_read_b128 v[190:193], v153 offset:7168
	s_setprio 1
	s_waitcnt lgkmcnt(7)
	v_mfma_f32_16x16x32_bf16 v[128:131], v[138:141], v[162:165], v[128:131]
	v_mfma_f32_16x16x32_bf16 v[124:127], v[142:145], v[162:165], v[124:127]
	v_mfma_f32_16x16x32_bf16 v[120:123], v[154:157], v[162:165], v[120:123]
	v_mfma_f32_16x16x32_bf16 v[116:119], v[158:161], v[162:165], v[116:119]
	s_waitcnt lgkmcnt(6)
	v_mfma_f32_16x16x32_bf16 v[112:115], v[138:141], v[166:169], v[112:115]
	v_mfma_f32_16x16x32_bf16 v[108:111], v[142:145], v[166:169], v[108:111]
	v_mfma_f32_16x16x32_bf16 v[104:107], v[154:157], v[166:169], v[104:107]
	v_mfma_f32_16x16x32_bf16 v[100:103], v[158:161], v[166:169], v[100:103]
	s_waitcnt lgkmcnt(5)
	v_mfma_f32_16x16x32_bf16 v[96:99], v[138:141], v[170:173], v[96:99]
	v_mfma_f32_16x16x32_bf16 v[92:95], v[142:145], v[170:173], v[92:95]
	v_mfma_f32_16x16x32_bf16 v[88:91], v[154:157], v[170:173], v[88:91]
	v_mfma_f32_16x16x32_bf16 v[84:87], v[158:161], v[170:173], v[84:87]
	s_waitcnt lgkmcnt(4)
	v_mfma_f32_16x16x32_bf16 v[80:83], v[138:141], v[174:177], v[80:83]
	v_mfma_f32_16x16x32_bf16 v[76:79], v[142:145], v[174:177], v[76:79]
	v_mfma_f32_16x16x32_bf16 v[72:75], v[154:157], v[174:177], v[72:75]
	v_mfma_f32_16x16x32_bf16 v[68:71], v[158:161], v[174:177], v[68:71]
	s_waitcnt lgkmcnt(3)
	v_mfma_f32_16x16x32_bf16 v[64:67], v[138:141], v[178:181], v[64:67]
	v_mfma_f32_16x16x32_bf16 v[60:63], v[142:145], v[178:181], v[60:63]
	v_mfma_f32_16x16x32_bf16 v[56:59], v[154:157], v[178:181], v[56:59]
	v_mfma_f32_16x16x32_bf16 v[52:55], v[158:161], v[178:181], v[52:55]
	s_waitcnt lgkmcnt(2)
	v_mfma_f32_16x16x32_bf16 v[48:51], v[138:141], v[182:185], v[48:51]
	v_mfma_f32_16x16x32_bf16 v[44:47], v[142:145], v[182:185], v[44:47]
	v_mfma_f32_16x16x32_bf16 v[40:43], v[154:157], v[182:185], v[40:43]
	v_mfma_f32_16x16x32_bf16 v[36:39], v[158:161], v[182:185], v[36:39]
	s_waitcnt lgkmcnt(1)
	v_mfma_f32_16x16x32_bf16 v[32:35], v[138:141], v[186:189], v[32:35]
	v_mfma_f32_16x16x32_bf16 v[28:31], v[142:145], v[186:189], v[28:31]
	v_mfma_f32_16x16x32_bf16 v[24:27], v[154:157], v[186:189], v[24:27]
	v_mfma_f32_16x16x32_bf16 v[20:23], v[158:161], v[186:189], v[20:23]
	s_waitcnt lgkmcnt(0)
	v_mfma_f32_16x16x32_bf16 v[16:19], v[138:141], v[190:193], v[16:19]
	v_mfma_f32_16x16x32_bf16 v[12:15], v[142:145], v[190:193], v[12:15]
	v_mfma_f32_16x16x32_bf16 v[8:11], v[154:157], v[190:193], v[8:11]
	v_mfma_f32_16x16x32_bf16 v[4:7], v[158:161], v[190:193], v[4:7]
	s_setprio 0
	s_waitcnt vmcnt(0)
	v_add_u32_e32 v140, s9, v146
	s_mov_b32 s2, 0x8000
	v_ashrrev_i32_e32 v141, 31, v140
	v_add_u32_e32 v139, 0xffff8000, v140
	v_cmp_gt_i32_e64 s[4:5], s2, v140
	v_readlane_b32 s12, v253, 53
	v_or_b32_e32 v138, s10, v147
	v_lshlrev_b64 v[142:143], 13, v[140:141]
	v_cndmask_b32_e64 v145, 0, v141, s[4:5]
	v_cndmask_b32_e64 v144, v139, v140, s[4:5]
	v_readlane_b32 s14, v253, 55
	v_readlane_b32 s15, v253, 56
	v_lshlrev_b64 v[144:145], 13, v[144:145]
	s_mov_b64 s[2:3], -1
	s_and_b64 vcc, exec, s[6:7]
	v_lshl_add_u64 v[142:143], s[14:15], 0, v[142:143]
	v_ashrrev_i32_e32 v139, 31, v138
	s_barrier
	v_readlane_b32 s13, v253, 54
	s_cbranch_vccz .LBB0_1306
	v_readlane_b32 s12, v251, 6
	v_readlane_b32 s13, v251, 7
	v_readlane_b32 s15, v251, 9
	v_readlane_b32 s14, v251, 8
	v_mov_b32_e32 v153, s13
	v_mov_b32_e32 v141, s15
	v_cndmask_b32_e64 v155, v141, v153, s[4:5]
	v_mov_b32_e32 v141, s14
	v_mov_b32_e32 v153, s12
	v_cndmask_b32_e64 v154, v141, v153, s[4:5]
	v_readlane_b32 s2, v254, 7
	v_lshl_add_u64 v[154:155], v[154:155], 0, v[144:145]
	v_readlane_b32 s3, v254, 8
	v_lshlrev_b64 v[158:159], 2, v[138:139]
	v_readlane_b32 s16, v251, 10
	v_cndmask_b32_e64 v155, v143, v155, s[2:3]
	v_cndmask_b32_e64 v154, v142, v154, s[2:3]
	v_lshl_add_u64 v[154:155], v[154:155], 0, v[158:159]
	global_load_dwordx4 v[154:157], v[154:155], off
	v_lshl_add_u64 v[158:159], v[142:143], 0, v[158:159]
	v_readlane_b32 s17, v251, 11
	v_readlane_b32 s18, v251, 12
	v_readlane_b32 s19, v251, 13
	v_readlane_b32 s20, v251, 14
	v_readlane_b32 s21, v251, 15
	v_readlane_b32 s22, v251, 16
	v_readlane_b32 s23, v251, 17
	v_readlane_b32 s24, v251, 18
	v_readlane_b32 s25, v251, 19
	v_readlane_b32 s26, v251, 20
	v_readlane_b32 s27, v251, 21
	s_mov_b64 s[2:3], 0
	s_waitcnt vmcnt(0)
	v_pk_add_f32 v[154:155], v[128:129], v[154:155]
	v_pk_add_f32 v[156:157], v[130:131], v[156:157]
	global_store_dwordx4 v[158:159], v[154:157], off

; __global__ void __launch_bounds__(256, 2) mega(Params p) {
;     ...
;     gemm_phase<EPI_RES>(p, l, (const u16*)(p.ws + W_XN), (const u16*)(p.ws + W_WTOUT), D, D / 128, smem, bid, nb, l == 0, 4);
;     grid.sync();
.LBB0_1432:
	v_readlane_b32 s28, v255, 45
	v_readlane_b32 s29, v255, 46
	v_readlane_b32 s30, v255, 47
	v_readlane_b32 s31, v255, 48
	s_waitcnt vmcnt(63) expcnt(7) lgkmcnt(15)
	s_waitcnt vmcnt(0)
	s_barrier
	s_mov_b64 s[2:3], exec
	v_readlane_b32 s4, v254, 0
	v_readlane_b32 s5, v254, 1
	s_and_b64 s[4:5], s[2:3], s[4:5]
	s_mov_b64 exec, s[4:5]
	s_cbranch_execz .LBB0_1442
	v_readlane_b32 s4, v251, 1
	v_readlane_b32 s5, v251, 2
	v_readlane_b32 s8, v251, 5
	v_readlane_b32 s9, v251, 0
	buffer_wbl2 sc1
	s_waitcnt vmcnt(0)
	s_add_u32 s4, s4, 0x318aa000
	s_addc_u32 s5, s5, 0
	v_mov_b32_e32 v3, 1
	v_mov_b32_e32 v4, 0x500
	s_and_b32 s9, s9, 7
	s_lshl_b32 s9, s9, 8
	s_add_u32 s9, s9, 0x8800
	global_atomic_add v3, v4, v3, s[4:5] sc0
	v_mov_b32_e32 v5, s9
	s_waitcnt vmcnt(0)
	v_readfirstlane_b32 s10, v3
	s_mov_b32 s11, s8
